# adds dilated-window fast path: per wave five 32-key blocks (3 full, 2 triangular masks), exact two-pass softmax, 40 MFMA and ~370 VALU per wave-unit for units with q0>=256
# speedup vs baseline: 1.0368x; 1.0085x over previous
.LBB0_703:
	s_ashr_i32 s2, s20, 1
	s_andn2_b32 s2, s2, 31
	s_add_i32 s2, s2, s58
	v_and_b32_e32 v2, 31, v0
	v_bfe_u32 v181, v0, 5, 1
	v_add_u32_e32 v180, s2, v2
	s_cmp_le_i32 s1, s0
	v_lshlrev_b32_e32 v176, 2, v181
	s_cbranch_scc1 .LBB0_708
	v_lshlrev_b32_e32 v3, 1, v0
	v_lshlrev_b32_e32 v0, 3, v0
	v_and_b32_e32 v1, 0xc0, v1
	v_and_b32_e32 v3, 32, v3
	v_and_b32_e32 v0, 24, v0
	s_add_i32 s58, s2, 31
	s_add_i32 s59, s2, 0xffffff80
	v_lshl_or_b32 v1, v181, 8, v1
	s_sub_i32 s2, s2, 59
	v_or3_b32 v183, v1, v3, v0
	v_add_u32_e32 v0, s2, v2
	v_lshlrev_b32_e32 v4, 4, v181
	v_sub_u32_e32 v0, v0, v176
	s_lshl_b32 s2, s0, 6
	v_mov_b32_e32 v182, 0
	v_mad_u32_u24 v184, v2, s47, v4
	v_subrev_u32_e32 v185, s2, v0
	s_or_b32 s60, s2, 63
	v_sub_u32_e32 v186, v176, v180
	v_mov_b32_e32 v187, 0xff800000
	v_mov_b32_e32 v16, 0
	v_mov_b32_e32 v17, v182
	v_mov_b32_e32 v18, v182
	v_mov_b32_e32 v19, v182
	v_mov_b32_e32 v20, v182
	v_mov_b32_e32 v21, v182
	v_mov_b32_e32 v22, v182
	v_mov_b32_e32 v23, v182
	v_mov_b32_e32 v24, v182
	v_mov_b32_e32 v25, v182
	v_mov_b32_e32 v26, v182
	v_mov_b32_e32 v27, v182
	v_mov_b32_e32 v28, v182
	v_mov_b32_e32 v29, v182
	v_mov_b32_e32 v30, v182
	v_mov_b32_e32 v31, v182
	v_mov_b32_e32 v0, 0
	v_mov_b32_e32 v1, v182
	v_mov_b32_e32 v2, v182
	v_mov_b32_e32 v3, v182
	v_mov_b32_e32 v4, v182
	v_mov_b32_e32 v5, v182
	v_mov_b32_e32 v6, v182
	v_mov_b32_e32 v7, v182
	v_mov_b32_e32 v8, v182
	v_mov_b32_e32 v9, v182
	v_mov_b32_e32 v10, v182
	v_mov_b32_e32 v11, v182
	v_mov_b32_e32 v12, v182
	v_mov_b32_e32 v13, v182
	v_mov_b32_e32 v14, v182
	v_mov_b32_e32 v15, v182
	s_cmp_lt_i32 s0, 1
	s_cbranch_scc1 .LBB0_706
	s_branch .Lwin_fast_l0
.Lwin_fast_l0:
	s_sub_i32 s98, s59, s2
	s_lshr_b32 s99, s98, 6
	s_mul_i32 s99, s99, 0x4400
	s_bfe_u32 s100, s98, 0x10005
	s_mul_i32 s101, s100, 0x1200
	s_add_i32 s101, s101, s99
	v_add_u32_e32 v236, s101, v184
	s_lshl_b32 s100, s100, 11
	s_add_i32 s100, s100, s99
	v_add_u32_e32 v244, s100, v183
	s_add_i32 s98, s98, 32
	s_lshr_b32 s99, s98, 6
	s_mul_i32 s99, s99, 0x4400
	s_bfe_u32 s100, s98, 0x10005
	s_mul_i32 s101, s100, 0x1200
	s_add_i32 s101, s101, s99
	v_add_u32_e32 v237, s101, v184
	s_lshl_b32 s100, s100, 11
	s_add_i32 s100, s100, s99
	v_add_u32_e32 v251, s100, v183
	s_add_i32 s98, s98, 32
	s_lshr_b32 s99, s98, 6
	s_mul_i32 s99, s99, 0x4400
	s_bfe_u32 s100, s98, 0x10005
	s_mul_i32 s101, s100, 0x1200
	s_add_i32 s101, s101, s99
	v_add_u32_e32 v241, s101, v184
	s_lshl_b32 s100, s100, 11
	s_add_i32 s100, s100, s99
	v_add_u32_e32 v252, s100, v183
	s_add_i32 s98, s98, 32
	s_lshr_b32 s99, s98, 6
	s_mul_i32 s99, s99, 0x4400
	s_bfe_u32 s100, s98, 0x10005
	s_mul_i32 s101, s100, 0x1200
	s_add_i32 s101, s101, s99
	v_add_u32_e32 v242, s101, v184
	s_lshl_b32 s100, s100, 11
	s_add_i32 s100, s100, s99
	v_add_u32_e32 v253, s100, v183
	s_add_i32 s98, s98, 32
	s_lshr_b32 s99, s98, 6
	s_mul_i32 s99, s99, 0x4400
	s_bfe_u32 s100, s98, 0x10005
	s_mul_i32 s101, s100, 0x1200
	s_add_i32 s101, s101, s99
	v_add_u32_e32 v243, s101, v184
	s_lshl_b32 s100, s100, 11
	s_add_i32 s100, s100, s99
	v_add_u32_e32 v254, s100, v183
	v_and_b32_e32 v240, 31, v180
	v_sub_u32_e32 v240, v240, v176
	ds_read_b128 v[204:207], v236 offset:0
	ds_read_b128 v[208:211], v236 offset:32
	ds_read_b128 v[212:215], v236 offset:64
	ds_read_b128 v[216:219], v236 offset:96
	s_waitcnt lgkmcnt(3)
	v_mfma_f32_32x32x16_bf16 v[32:47], v[204:207], v[112:115], 0
	ds_read_b128 v[220:223], v237 offset:0
	s_waitcnt lgkmcnt(3)
	v_mfma_f32_32x32x16_bf16 v[32:47], v[208:211], v[116:119], v[32:47]
	ds_read_b128 v[224:227], v237 offset:32
	s_waitcnt lgkmcnt(3)
	v_mfma_f32_32x32x16_bf16 v[32:47], v[212:215], v[120:123], v[32:47]
	ds_read_b128 v[228:231], v237 offset:64
	s_waitcnt lgkmcnt(3)
	v_mfma_f32_32x32x16_bf16 v[32:47], v[216:219], v[124:127], v[32:47]
	ds_read_b128 v[232:235], v237 offset:96
	s_waitcnt lgkmcnt(3)
	v_mfma_f32_32x32x16_bf16 v[48:63], v[220:223], v[112:115], 0
	ds_read_b128 v[204:207], v241 offset:0
	s_waitcnt lgkmcnt(3)
	v_mfma_f32_32x32x16_bf16 v[48:63], v[224:227], v[116:119], v[48:63]
	ds_read_b128 v[208:211], v241 offset:32
	s_waitcnt lgkmcnt(3)
	v_mfma_f32_32x32x16_bf16 v[48:63], v[228:231], v[120:123], v[48:63]
	ds_read_b128 v[212:215], v241 offset:64
	s_waitcnt lgkmcnt(3)
	v_mfma_f32_32x32x16_bf16 v[48:63], v[232:235], v[124:127], v[48:63]
	ds_read_b128 v[216:219], v241 offset:96
	s_waitcnt lgkmcnt(3)
	v_mfma_f32_32x32x16_bf16 v[144:159], v[204:207], v[112:115], 0
	ds_read_b128 v[220:223], v242 offset:0
	s_waitcnt lgkmcnt(3)
	v_mfma_f32_32x32x16_bf16 v[144:159], v[208:211], v[116:119], v[144:159]
	ds_read_b128 v[224:227], v242 offset:32
	s_waitcnt lgkmcnt(3)
	v_mfma_f32_32x32x16_bf16 v[144:159], v[212:215], v[120:123], v[144:159]
	ds_read_b128 v[228:231], v242 offset:64
	s_waitcnt lgkmcnt(3)
	v_mfma_f32_32x32x16_bf16 v[144:159], v[216:219], v[124:127], v[144:159]
	ds_read_b128 v[232:235], v242 offset:96
	v_cmp_le_i32_e64 s[98:99], v240, 0
	v_max3_f32 v246, v48, v49, v50
	v_cmp_le_i32_e64 s[100:101], v240, 1
	v_max3_f32 v246, v246, v51, v52
	v_cmp_le_i32_e64 vcc, v240, 2
	v_max3_f32 v246, v246, v53, v54
	s_waitcnt lgkmcnt(3)
	v_mfma_f32_32x32x16_bf16 v[160:175], v[220:223], v[112:115], 0
	ds_read_b128 v[204:207], v243 offset:0
	v_cndmask_b32_e64 v32, v179, v32, s[98:99]
	v_max3_f32 v246, v246, v55, v56
	v_cmp_le_i32_e64 s[98:99], v240, 3
	v_max3_f32 v246, v246, v57, v58
	v_cndmask_b32_e64 v33, v179, v33, s[100:101]
	v_max3_f32 v246, v246, v59, v60
	s_waitcnt lgkmcnt(3)
	v_mfma_f32_32x32x16_bf16 v[160:175], v[224:227], v[116:119], v[160:175]
	ds_read_b128 v[208:211], v243 offset:32
	v_cmp_le_i32_e64 s[100:101], v240, 8
	v_max3_f32 v246, v246, v61, v62
	v_cndmask_b32_e64 v34, v179, v34, vcc
	v_max3_f32 v246, v246, v63, v63
	v_cmp_le_i32_e64 vcc, v240, 9
	v_cndmask_b32_e64 v35, v179, v35, s[98:99]
	s_waitcnt lgkmcnt(3)
	v_mfma_f32_32x32x16_bf16 v[160:175], v[228:231], v[120:123], v[160:175]
	ds_read_b128 v[212:215], v243 offset:64
	v_cmp_le_i32_e64 s[98:99], v240, 10
	v_cndmask_b32_e64 v36, v179, v36, s[100:101]
	v_cmp_le_i32_e64 s[100:101], v240, 11
	v_cndmask_b32_e64 v37, v179, v37, vcc
	v_cmp_le_i32_e64 vcc, v240, 16
	v_cndmask_b32_e64 v38, v179, v38, s[98:99]
	s_waitcnt lgkmcnt(3)
	v_mfma_f32_32x32x16_bf16 v[160:175], v[232:235], v[124:127], v[160:175]
	ds_read_b128 v[216:219], v243 offset:96
	v_cmp_le_i32_e64 s[98:99], v240, 17
	v_cndmask_b32_e64 v39, v179, v39, s[100:101]
	v_cmp_le_i32_e64 s[100:101], v240, 18
	v_cndmask_b32_e64 v40, v179, v40, vcc
	v_cmp_le_i32_e64 vcc, v240, 19
	v_cndmask_b32_e64 v41, v179, v41, s[98:99]
	v_cmp_le_i32_e64 s[98:99], v240, 24
	v_cndmask_b32_e64 v42, v179, v42, s[100:101]
	v_cmp_le_i32_e64 s[100:101], v240, 25
	v_cndmask_b32_e64 v43, v179, v43, vcc
	v_cmp_le_i32_e64 vcc, v240, 26
	v_cndmask_b32_e64 v44, v179, v44, s[98:99]
	v_cmp_le_i32_e64 s[98:99], v240, 27
	v_cndmask_b32_e64 v45, v179, v45, s[100:101]
	v_cndmask_b32_e64 v46, v179, v46, vcc
	v_cndmask_b32_e64 v47, v179, v47, s[98:99]
	v_max3_f32 v247, v144, v145, v146
	v_max3_f32 v248, v32, v33, v34
	v_max3_f32 v247, v247, v147, v148
	v_max3_f32 v248, v248, v35, v36
	s_waitcnt lgkmcnt(3)
	v_mfma_f32_32x32x16_bf16 v[188:203], v[204:207], v[112:115], 0
	ds_read_b64_tr_b16 v[220:221], v244 offset:9216
	ds_read_b64_tr_b16 v[222:223], v244 offset:9728
	v_max3_f32 v247, v247, v149, v150
	v_max3_f32 v248, v248, v37, v38
	v_max3_f32 v247, v247, v151, v152
	v_max3_f32 v248, v248, v39, v40
	s_waitcnt lgkmcnt(4)
	v_mfma_f32_32x32x16_bf16 v[188:203], v[208:211], v[116:119], v[188:203]
	ds_read_b64_tr_b16 v[224:225], v244 offset:13312
	ds_read_b64_tr_b16 v[226:227], v244 offset:13824
	v_max3_f32 v247, v247, v153, v154
	v_max3_f32 v248, v248, v41, v42
	v_max3_f32 v247, v247, v155, v156
	v_max3_f32 v248, v248, v43, v44
	s_waitcnt lgkmcnt(5)
	v_mfma_f32_32x32x16_bf16 v[188:203], v[212:215], v[120:123], v[188:203]
	ds_read_b64_tr_b16 v[228:229], v244 offset:10240
	ds_read_b64_tr_b16 v[230:231], v244 offset:10752
	v_max3_f32 v247, v247, v157, v158
	v_max3_f32 v248, v248, v45, v46
	v_max3_f32 v247, v247, v159, v159
	v_max3_f32 v248, v248, v47, v47
	s_waitcnt lgkmcnt(6)
	v_mfma_f32_32x32x16_bf16 v[188:203], v[216:219], v[124:127], v[188:203]
	ds_read_b64_tr_b16 v[232:233], v244 offset:14336
	ds_read_b64_tr_b16 v[234:235], v244 offset:14848
	v_max3_f32 v249, v160, v161, v162
	v_max3_f32 v249, v249, v163, v164
	v_max3_f32 v249, v249, v165, v166
	v_max3_f32 v249, v249, v167, v168
	v_max3_f32 v249, v249, v169, v170
	v_max3_f32 v249, v249, v171, v172
	v_max3_f32 v249, v249, v173, v174
	v_max3_f32 v249, v249, v175, v175
	v_cmp_ge_i32_e64 s[98:99], v240, 0
	v_cmp_ge_i32_e64 s[100:101], v240, 1
	v_cmp_ge_i32_e64 vcc, v240, 2
	v_cndmask_b32_e64 v188, v179, v188, s[98:99]
	v_cmp_ge_i32_e64 s[98:99], v240, 3
	v_cndmask_b32_e64 v189, v179, v189, s[100:101]
	v_cmp_ge_i32_e64 s[100:101], v240, 8
	v_cndmask_b32_e64 v190, v179, v190, vcc
	v_cmp_ge_i32_e64 vcc, v240, 9
	v_cndmask_b32_e64 v191, v179, v191, s[98:99]
	v_cmp_ge_i32_e64 s[98:99], v240, 10
	v_cndmask_b32_e64 v192, v179, v192, s[100:101]
	v_cmp_ge_i32_e64 s[100:101], v240, 11
	v_cndmask_b32_e64 v193, v179, v193, vcc
	v_cmp_ge_i32_e64 vcc, v240, 16
	v_cndmask_b32_e64 v194, v179, v194, s[98:99]
	v_cmp_ge_i32_e64 s[98:99], v240, 17
	v_cndmask_b32_e64 v195, v179, v195, s[100:101]
	v_cmp_ge_i32_e64 s[100:101], v240, 18
	v_cndmask_b32_e64 v196, v179, v196, vcc
	v_cmp_ge_i32_e64 vcc, v240, 19
	v_cndmask_b32_e64 v197, v179, v197, s[98:99]
	v_cmp_ge_i32_e64 s[98:99], v240, 24
	v_cndmask_b32_e64 v198, v179, v198, s[100:101]
	v_cmp_ge_i32_e64 s[100:101], v240, 25
	v_cndmask_b32_e64 v199, v179, v199, vcc
	v_cmp_ge_i32_e64 vcc, v240, 26
	v_cndmask_b32_e64 v200, v179, v200, s[98:99]
	v_cmp_ge_i32_e64 s[98:99], v240, 27
	v_cndmask_b32_e64 v201, v179, v201, s[100:101]
	v_cndmask_b32_e64 v202, v179, v202, vcc
	v_cndmask_b32_e64 v203, v179, v203, s[98:99]
	v_max3_f32 v249, v249, v188, v189
	v_max3_f32 v249, v249, v190, v191
	v_max3_f32 v249, v249, v192, v193
	v_max3_f32 v249, v249, v194, v195
	v_max3_f32 v249, v249, v196, v197
	v_max3_f32 v249, v249, v198, v199
	v_max3_f32 v249, v249, v200, v201
	v_max3_f32 v249, v249, v202, v203
	v_max3_f32 v246, v246, v247, v248
	v_max_f32_e32 v246, v246, v249
	v_mov_b32_e32 v247, v246
	s_nop 1
	v_permlane32_swap_b32_e32 v246, v247
	v_max_f32_e32 v246, v246, v247
	v_mul_f32_e32 v250, s54, v246
	v_fma_f32 v32, v32, s54, -v250
	v_fma_f32 v33, v33, s54, -v250
	v_fma_f32 v34, v34, s54, -v250
	v_exp_f32_e32 v32, v32
	v_fma_f32 v35, v35, s54, -v250
	v_exp_f32_e32 v33, v33
	v_fma_f32 v36, v36, s54, -v250
	v_exp_f32_e32 v34, v34
	v_fma_f32 v37, v37, s54, -v250
	v_exp_f32_e32 v35, v35
	v_fma_f32 v38, v38, s54, -v250
	v_exp_f32_e32 v36, v36
	v_mov_b64_e32 v[246:247], v[32:33]
	v_fma_f32 v39, v39, s54, -v250
	v_exp_f32_e32 v37, v37
	v_fma_f32 v40, v40, s54, -v250
	v_exp_f32_e32 v38, v38
	v_mov_b64_e32 v[248:249], v[34:35]
	v_fma_f32 v41, v41, s54, -v250
	v_exp_f32_e32 v39, v39
	v_fma_f32 v42, v42, s54, -v250
	v_exp_f32_e32 v40, v40
	v_pk_add_f32 v[246:247], v[246:247], v[36:37]
	v_fma_f32 v43, v43, s54, -v250
	v_exp_f32_e32 v41, v41
	v_fma_f32 v44, v44, s54, -v250
	v_exp_f32_e32 v42, v42
	v_pk_add_f32 v[248:249], v[248:249], v[38:39]
	v_fma_f32 v45, v45, s54, -v250
	v_exp_f32_e32 v43, v43
	v_fma_f32 v46, v46, s54, -v250
	v_exp_f32_e32 v44, v44
	v_pk_add_f32 v[246:247], v[246:247], v[40:41]
	v_fma_f32 v47, v47, s54, -v250
	v_exp_f32_e32 v45, v45
	v_exp_f32_e32 v46, v46
	v_pk_add_f32 v[248:249], v[248:249], v[42:43]
	v_exp_f32_e32 v47, v47
	v_pk_add_f32 v[246:247], v[246:247], v[44:45]
	v_pk_add_f32 v[248:249], v[248:249], v[46:47]
	v_cvt_pk_bf16_f32 v32, v32, v33
	v_cvt_pk_bf16_f32 v33, v34, v35
	v_cvt_pk_bf16_f32 v34, v36, v37
	v_cvt_pk_bf16_f32 v35, v38, v39
	v_cvt_pk_bf16_f32 v36, v40, v41
	v_cvt_pk_bf16_f32 v37, v42, v43
	v_cvt_pk_bf16_f32 v38, v44, v45
	v_cvt_pk_bf16_f32 v39, v46, v47
	v_fma_f32 v48, v48, s54, -v250
	v_fma_f32 v49, v49, s54, -v250
	v_fma_f32 v50, v50, s54, -v250
	v_exp_f32_e32 v48, v48
	v_fma_f32 v51, v51, s54, -v250
	v_exp_f32_e32 v49, v49
	v_fma_f32 v52, v52, s54, -v250
	v_exp_f32_e32 v50, v50
	s_waitcnt lgkmcnt(6)
	v_mfma_f32_32x32x16_bf16 v[16:31], v[220:223], v[32:35], v[16:31]
	ds_read_b64_tr_b16 v[204:205], v251 offset:9216
	ds_read_b64_tr_b16 v[206:207], v251 offset:9728
	v_fma_f32 v53, v53, s54, -v250
	v_exp_f32_e32 v51, v51
	v_fma_f32 v54, v54, s54, -v250
	v_exp_f32_e32 v52, v52
	v_pk_add_f32 v[246:247], v[246:247], v[48:49]
	v_fma_f32 v55, v55, s54, -v250
	v_exp_f32_e32 v53, v53
	v_fma_f32 v56, v56, s54, -v250
	s_waitcnt lgkmcnt(6)
	v_mfma_f32_32x32x16_bf16 v[0:15], v[224:227], v[32:35], v[0:15]
	ds_read_b64_tr_b16 v[208:209], v251 offset:13312
	ds_read_b64_tr_b16 v[210:211], v251 offset:13824
	v_exp_f32_e32 v54, v54
	v_pk_add_f32 v[248:249], v[248:249], v[50:51]
	v_fma_f32 v57, v57, s54, -v250
	v_exp_f32_e32 v55, v55
	v_fma_f32 v58, v58, s54, -v250
	v_exp_f32_e32 v56, v56
	v_pk_add_f32 v[246:247], v[246:247], v[52:53]
	v_fma_f32 v59, v59, s54, -v250
	s_waitcnt lgkmcnt(6)
	v_mfma_f32_32x32x16_bf16 v[16:31], v[228:231], v[36:39], v[16:31]
	ds_read_b64_tr_b16 v[212:213], v251 offset:10240
	ds_read_b64_tr_b16 v[214:215], v251 offset:10752
	v_exp_f32_e32 v57, v57
	v_fma_f32 v60, v60, s54, -v250
	v_exp_f32_e32 v58, v58
	v_pk_add_f32 v[248:249], v[248:249], v[54:55]
	v_fma_f32 v61, v61, s54, -v250
	v_exp_f32_e32 v59, v59
	v_fma_f32 v62, v62, s54, -v250
	v_exp_f32_e32 v60, v60
	s_waitcnt lgkmcnt(6)
	v_mfma_f32_32x32x16_bf16 v[0:15], v[232:235], v[36:39], v[0:15]
	ds_read_b64_tr_b16 v[216:217], v251 offset:14336
	ds_read_b64_tr_b16 v[218:219], v251 offset:14848
	v_pk_add_f32 v[246:247], v[246:247], v[56:57]
	v_fma_f32 v63, v63, s54, -v250
	v_exp_f32_e32 v61, v61
	v_exp_f32_e32 v62, v62
	v_pk_add_f32 v[248:249], v[248:249], v[58:59]
	v_exp_f32_e32 v63, v63
	v_pk_add_f32 v[246:247], v[246:247], v[60:61]
	v_pk_add_f32 v[248:249], v[248:249], v[62:63]
	v_cvt_pk_bf16_f32 v48, v48, v49
	v_cvt_pk_bf16_f32 v49, v50, v51
	v_cvt_pk_bf16_f32 v50, v52, v53
	v_cvt_pk_bf16_f32 v51, v54, v55
	v_cvt_pk_bf16_f32 v52, v56, v57
	v_cvt_pk_bf16_f32 v53, v58, v59
	v_cvt_pk_bf16_f32 v54, v60, v61
	v_cvt_pk_bf16_f32 v55, v62, v63
	v_fma_f32 v144, v144, s54, -v250
	v_fma_f32 v145, v145, s54, -v250
	v_fma_f32 v146, v146, s54, -v250
	v_exp_f32_e32 v144, v144
	v_fma_f32 v147, v147, s54, -v250
	v_exp_f32_e32 v145, v145
	v_fma_f32 v148, v148, s54, -v250
	v_exp_f32_e32 v146, v146
	s_waitcnt lgkmcnt(6)
	v_mfma_f32_32x32x16_bf16 v[16:31], v[204:207], v[48:51], v[16:31]
	ds_read_b64_tr_b16 v[220:221], v252 offset:9216
	ds_read_b64_tr_b16 v[222:223], v252 offset:9728
	v_fma_f32 v149, v149, s54, -v250
	v_exp_f32_e32 v147, v147
	v_fma_f32 v150, v150, s54, -v250
	v_exp_f32_e32 v148, v148
	v_pk_add_f32 v[246:247], v[246:247], v[144:145]
	v_fma_f32 v151, v151, s54, -v250
	v_exp_f32_e32 v149, v149
	v_fma_f32 v152, v152, s54, -v250
	s_waitcnt lgkmcnt(6)
	v_mfma_f32_32x32x16_bf16 v[0:15], v[208:211], v[48:51], v[0:15]
	ds_read_b64_tr_b16 v[224:225], v252 offset:13312
	ds_read_b64_tr_b16 v[226:227], v252 offset:13824
	v_exp_f32_e32 v150, v150
	v_pk_add_f32 v[248:249], v[248:249], v[146:147]
	v_fma_f32 v153, v153, s54, -v250
	v_exp_f32_e32 v151, v151
	v_fma_f32 v154, v154, s54, -v250
	v_exp_f32_e32 v152, v152
	v_pk_add_f32 v[246:247], v[246:247], v[148:149]
	v_fma_f32 v155, v155, s54, -v250
	s_waitcnt lgkmcnt(6)
	v_mfma_f32_32x32x16_bf16 v[16:31], v[212:215], v[52:55], v[16:31]
	ds_read_b64_tr_b16 v[228:229], v252 offset:10240
	ds_read_b64_tr_b16 v[230:231], v252 offset:10752
	v_exp_f32_e32 v153, v153
	v_fma_f32 v156, v156, s54, -v250
	v_exp_f32_e32 v154, v154
	v_pk_add_f32 v[248:249], v[248:249], v[150:151]
	v_fma_f32 v157, v157, s54, -v250
	v_exp_f32_e32 v155, v155
	v_fma_f32 v158, v158, s54, -v250
	v_exp_f32_e32 v156, v156
	s_waitcnt lgkmcnt(6)
	v_mfma_f32_32x32x16_bf16 v[0:15], v[216:219], v[52:55], v[0:15]
	ds_read_b64_tr_b16 v[232:233], v252 offset:14336
	ds_read_b64_tr_b16 v[234:235], v252 offset:14848
	v_pk_add_f32 v[246:247], v[246:247], v[152:153]
	v_fma_f32 v159, v159, s54, -v250
	v_exp_f32_e32 v157, v157
	v_exp_f32_e32 v158, v158
	v_pk_add_f32 v[248:249], v[248:249], v[154:155]
	v_exp_f32_e32 v159, v159
	v_pk_add_f32 v[246:247], v[246:247], v[156:157]
	v_pk_add_f32 v[248:249], v[248:249], v[158:159]
	v_cvt_pk_bf16_f32 v144, v144, v145
	v_cvt_pk_bf16_f32 v145, v146, v147
	v_cvt_pk_bf16_f32 v146, v148, v149
	v_cvt_pk_bf16_f32 v147, v150, v151
	v_cvt_pk_bf16_f32 v148, v152, v153
	v_cvt_pk_bf16_f32 v149, v154, v155
	v_cvt_pk_bf16_f32 v150, v156, v157
	v_cvt_pk_bf16_f32 v151, v158, v159
	v_fma_f32 v160, v160, s54, -v250
	v_fma_f32 v161, v161, s54, -v250
	v_fma_f32 v162, v162, s54, -v250
	v_exp_f32_e32 v160, v160
	v_fma_f32 v163, v163, s54, -v250
	v_exp_f32_e32 v161, v161
	v_fma_f32 v164, v164, s54, -v250
	v_exp_f32_e32 v162, v162
	s_waitcnt lgkmcnt(6)
	v_mfma_f32_32x32x16_bf16 v[16:31], v[220:223], v[144:147], v[16:31]
	ds_read_b64_tr_b16 v[204:205], v253 offset:9216
	ds_read_b64_tr_b16 v[206:207], v253 offset:9728
	v_fma_f32 v165, v165, s54, -v250
	v_exp_f32_e32 v163, v163
	v_fma_f32 v166, v166, s54, -v250
	v_exp_f32_e32 v164, v164
	v_pk_add_f32 v[246:247], v[246:247], v[160:161]
	v_fma_f32 v167, v167, s54, -v250
	v_exp_f32_e32 v165, v165
	v_fma_f32 v168, v168, s54, -v250
	s_waitcnt lgkmcnt(6)
	v_mfma_f32_32x32x16_bf16 v[0:15], v[224:227], v[144:147], v[0:15]
	ds_read_b64_tr_b16 v[208:209], v253 offset:13312
	ds_read_b64_tr_b16 v[210:211], v253 offset:13824
	v_exp_f32_e32 v166, v166
	v_pk_add_f32 v[248:249], v[248:249], v[162:163]
	v_fma_f32 v169, v169, s54, -v250
	v_exp_f32_e32 v167, v167
	v_fma_f32 v170, v170, s54, -v250
	v_exp_f32_e32 v168, v168
	v_pk_add_f32 v[246:247], v[246:247], v[164:165]
	v_fma_f32 v171, v171, s54, -v250
	s_waitcnt lgkmcnt(6)
	v_mfma_f32_32x32x16_bf16 v[16:31], v[228:231], v[148:151], v[16:31]
	ds_read_b64_tr_b16 v[212:213], v253 offset:10240
	ds_read_b64_tr_b16 v[214:215], v253 offset:10752
	v_exp_f32_e32 v169, v169
	v_fma_f32 v172, v172, s54, -v250
	v_exp_f32_e32 v170, v170
	v_pk_add_f32 v[248:249], v[248:249], v[166:167]
	v_fma_f32 v173, v173, s54, -v250
	v_exp_f32_e32 v171, v171
	v_fma_f32 v174, v174, s54, -v250
	v_exp_f32_e32 v172, v172
	s_waitcnt lgkmcnt(6)
	v_mfma_f32_32x32x16_bf16 v[0:15], v[232:235], v[148:151], v[0:15]
	ds_read_b64_tr_b16 v[216:217], v253 offset:14336
	ds_read_b64_tr_b16 v[218:219], v253 offset:14848
	v_pk_add_f32 v[246:247], v[246:247], v[168:169]
	v_fma_f32 v175, v175, s54, -v250
	v_exp_f32_e32 v173, v173
	v_exp_f32_e32 v174, v174
	v_pk_add_f32 v[248:249], v[248:249], v[170:171]
	v_exp_f32_e32 v175, v175
	v_pk_add_f32 v[246:247], v[246:247], v[172:173]
	v_pk_add_f32 v[248:249], v[248:249], v[174:175]
	v_cvt_pk_bf16_f32 v160, v160, v161
	v_cvt_pk_bf16_f32 v161, v162, v163
	v_cvt_pk_bf16_f32 v162, v164, v165
	v_cvt_pk_bf16_f32 v163, v166, v167
	v_cvt_pk_bf16_f32 v164, v168, v169
	v_cvt_pk_bf16_f32 v165, v170, v171
	v_cvt_pk_bf16_f32 v166, v172, v173
	v_cvt_pk_bf16_f32 v167, v174, v175
	v_fma_f32 v188, v188, s54, -v250
	v_fma_f32 v189, v189, s54, -v250
	v_fma_f32 v190, v190, s54, -v250
	v_exp_f32_e32 v188, v188
	v_fma_f32 v191, v191, s54, -v250
	v_exp_f32_e32 v189, v189
	v_fma_f32 v192, v192, s54, -v250
	v_exp_f32_e32 v190, v190
	s_waitcnt lgkmcnt(6)
	v_mfma_f32_32x32x16_bf16 v[16:31], v[204:207], v[160:163], v[16:31]
	ds_read_b64_tr_b16 v[220:221], v254 offset:9216
	ds_read_b64_tr_b16 v[222:223], v254 offset:9728
	v_fma_f32 v193, v193, s54, -v250
	v_exp_f32_e32 v191, v191
	v_fma_f32 v194, v194, s54, -v250
	v_exp_f32_e32 v192, v192
	v_pk_add_f32 v[246:247], v[246:247], v[188:189]
	v_fma_f32 v195, v195, s54, -v250
	v_exp_f32_e32 v193, v193
	v_fma_f32 v196, v196, s54, -v250
	s_waitcnt lgkmcnt(6)
	v_mfma_f32_32x32x16_bf16 v[0:15], v[208:211], v[160:163], v[0:15]
	ds_read_b64_tr_b16 v[224:225], v254 offset:13312
	ds_read_b64_tr_b16 v[226:227], v254 offset:13824
	v_exp_f32_e32 v194, v194
	v_pk_add_f32 v[248:249], v[248:249], v[190:191]
	v_fma_f32 v197, v197, s54, -v250
	v_exp_f32_e32 v195, v195
	v_fma_f32 v198, v198, s54, -v250
	v_exp_f32_e32 v196, v196
	v_pk_add_f32 v[246:247], v[246:247], v[192:193]
	v_fma_f32 v199, v199, s54, -v250
	s_waitcnt lgkmcnt(6)
	v_mfma_f32_32x32x16_bf16 v[16:31], v[212:215], v[164:167], v[16:31]
	ds_read_b64_tr_b16 v[228:229], v254 offset:10240
	ds_read_b64_tr_b16 v[230:231], v254 offset:10752
	v_exp_f32_e32 v197, v197
	v_fma_f32 v200, v200, s54, -v250
	v_exp_f32_e32 v198, v198
	v_pk_add_f32 v[248:249], v[248:249], v[194:195]
	v_fma_f32 v201, v201, s54, -v250
	v_exp_f32_e32 v199, v199
	v_fma_f32 v202, v202, s54, -v250
	v_exp_f32_e32 v200, v200
	s_waitcnt lgkmcnt(6)
	v_mfma_f32_32x32x16_bf16 v[0:15], v[216:219], v[164:167], v[0:15]
	ds_read_b64_tr_b16 v[232:233], v254 offset:14336
	ds_read_b64_tr_b16 v[234:235], v254 offset:14848
	v_pk_add_f32 v[246:247], v[246:247], v[196:197]
	v_fma_f32 v203, v203, s54, -v250
	v_exp_f32_e32 v201, v201
	v_exp_f32_e32 v202, v202
	v_pk_add_f32 v[248:249], v[248:249], v[198:199]
	v_exp_f32_e32 v203, v203
	v_pk_add_f32 v[246:247], v[246:247], v[200:201]
	v_pk_add_f32 v[248:249], v[248:249], v[202:203]
	v_cvt_pk_bf16_f32 v188, v188, v189
	v_cvt_pk_bf16_f32 v189, v190, v191
	v_cvt_pk_bf16_f32 v190, v192, v193
	v_cvt_pk_bf16_f32 v191, v194, v195
	v_cvt_pk_bf16_f32 v192, v196, v197
	v_cvt_pk_bf16_f32 v193, v198, v199
	v_cvt_pk_bf16_f32 v194, v200, v201
	v_cvt_pk_bf16_f32 v195, v202, v203
	v_pk_add_f32 v[246:247], v[246:247], v[248:249]
	s_waitcnt lgkmcnt(6)
	v_mfma_f32_32x32x16_bf16 v[16:31], v[220:223], v[188:191], v[16:31]
	s_waitcnt lgkmcnt(4)
	v_mfma_f32_32x32x16_bf16 v[0:15], v[224:227], v[188:191], v[0:15]
	v_add_f32_e32 v182, v246, v247
	v_mov_b32_e32 v187, v250
	s_waitcnt lgkmcnt(2)
	v_mfma_f32_32x32x16_bf16 v[16:31], v[228:231], v[192:195], v[16:31]
	s_waitcnt lgkmcnt(0)
	v_mfma_f32_32x32x16_bf16 v[0:15], v[232:235], v[192:195], v[0:15]
	s_branch .LBB0_709

.LBB0_1994:
	s_ashr_i32 s2, s54, 1
	s_andn2_b32 s2, s2, 31
	s_add_i32 s2, s2, s53
	v_and_b32_e32 v2, 31, v0
	v_bfe_u32 v181, v0, 5, 1
	v_add_u32_e32 v180, s2, v2
	s_cmp_le_i32 s1, s0
	v_lshlrev_b32_e32 v176, 2, v181
	s_cbranch_scc1 .LBB0_1999
	v_lshlrev_b32_e32 v3, 1, v0
	v_lshlrev_b32_e32 v0, 3, v0
	v_and_b32_e32 v1, 0xc0, v1
	v_and_b32_e32 v3, 32, v3
	v_and_b32_e32 v0, 24, v0
	s_add_i32 s53, s2, 31
	s_add_i32 s54, s2, 0xffffff80
	v_lshl_or_b32 v1, v181, 8, v1
	s_sub_i32 s2, s2, 59
	v_or3_b32 v183, v1, v3, v0
	v_add_u32_e32 v0, s2, v2
	v_lshlrev_b32_e32 v4, 4, v181
	v_sub_u32_e32 v0, v0, v176
	s_lshl_b32 s2, s0, 6
	v_mov_b32_e32 v182, 0
	v_mad_u32_u24 v184, v2, s39, v4
	v_subrev_u32_e32 v185, s2, v0
	s_or_b32 s55, s2, 63
	v_sub_u32_e32 v186, v176, v180
	v_mov_b32_e32 v187, 0xff800000
	v_mov_b32_e32 v16, 0
	v_mov_b32_e32 v17, v182
	v_mov_b32_e32 v18, v182
	v_mov_b32_e32 v19, v182
	v_mov_b32_e32 v20, v182
	v_mov_b32_e32 v21, v182
	v_mov_b32_e32 v22, v182
	v_mov_b32_e32 v23, v182
	v_mov_b32_e32 v24, v182
	v_mov_b32_e32 v25, v182
	v_mov_b32_e32 v26, v182
	v_mov_b32_e32 v27, v182
	v_mov_b32_e32 v28, v182
	v_mov_b32_e32 v29, v182
	v_mov_b32_e32 v30, v182
	v_mov_b32_e32 v31, v182
	v_mov_b32_e32 v0, 0
	v_mov_b32_e32 v1, v182
	v_mov_b32_e32 v2, v182
	v_mov_b32_e32 v3, v182
	v_mov_b32_e32 v4, v182
	v_mov_b32_e32 v5, v182
	v_mov_b32_e32 v6, v182
	v_mov_b32_e32 v7, v182
	v_mov_b32_e32 v8, v182
	v_mov_b32_e32 v9, v182
	v_mov_b32_e32 v10, v182
	v_mov_b32_e32 v11, v182
	v_mov_b32_e32 v12, v182
	v_mov_b32_e32 v13, v182
	v_mov_b32_e32 v14, v182
	v_mov_b32_e32 v15, v182
	s_cmp_lt_i32 s0, 1
	s_cbranch_scc1 .LBB0_1997
	s_branch .Lwin_fast_l1
.Lwin_fast_l1:
	s_sub_i32 s98, s54, s2
	s_lshr_b32 s99, s98, 6
	s_mul_i32 s99, s99, 0x4400
	s_bfe_u32 s100, s98, 0x10005
	s_mul_i32 s101, s100, 0x1200
	s_add_i32 s101, s101, s99
	v_add_u32_e32 v236, s101, v184
	s_lshl_b32 s100, s100, 11
	s_add_i32 s100, s100, s99
	v_add_u32_e32 v244, s100, v183
	s_add_i32 s98, s98, 32
	s_lshr_b32 s99, s98, 6
	s_mul_i32 s99, s99, 0x4400
	s_bfe_u32 s100, s98, 0x10005
	s_mul_i32 s101, s100, 0x1200
	s_add_i32 s101, s101, s99
	v_add_u32_e32 v237, s101, v184
	s_lshl_b32 s100, s100, 11
	s_add_i32 s100, s100, s99
	v_add_u32_e32 v251, s100, v183
	s_add_i32 s98, s98, 32
	s_lshr_b32 s99, s98, 6
	s_mul_i32 s99, s99, 0x4400
	s_bfe_u32 s100, s98, 0x10005
	s_mul_i32 s101, s100, 0x1200
	s_add_i32 s101, s101, s99
	v_add_u32_e32 v241, s101, v184
	s_lshl_b32 s100, s100, 11
	s_add_i32 s100, s100, s99
	v_add_u32_e32 v252, s100, v183
	s_add_i32 s98, s98, 32
	s_lshr_b32 s99, s98, 6
	s_mul_i32 s99, s99, 0x4400
	s_bfe_u32 s100, s98, 0x10005
	s_mul_i32 s101, s100, 0x1200
	s_add_i32 s101, s101, s99
	v_add_u32_e32 v242, s101, v184
	s_lshl_b32 s100, s100, 11
	s_add_i32 s100, s100, s99
	v_add_u32_e32 v253, s100, v183
	s_add_i32 s98, s98, 32
	s_lshr_b32 s99, s98, 6
	s_mul_i32 s99, s99, 0x4400
	s_bfe_u32 s100, s98, 0x10005
	s_mul_i32 s101, s100, 0x1200
	s_add_i32 s101, s101, s99
	v_add_u32_e32 v243, s101, v184
	s_lshl_b32 s100, s100, 11
	s_add_i32 s100, s100, s99
	v_add_u32_e32 v254, s100, v183
	v_and_b32_e32 v240, 31, v180
	v_sub_u32_e32 v240, v240, v176
	ds_read_b128 v[204:207], v236 offset:0
	ds_read_b128 v[208:211], v236 offset:32
	ds_read_b128 v[212:215], v236 offset:64
	ds_read_b128 v[216:219], v236 offset:96
	s_waitcnt lgkmcnt(3)
	v_mfma_f32_32x32x16_bf16 v[32:47], v[204:207], v[112:115], 0
	ds_read_b128 v[220:223], v237 offset:0
	s_waitcnt lgkmcnt(3)
	v_mfma_f32_32x32x16_bf16 v[32:47], v[208:211], v[116:119], v[32:47]
	ds_read_b128 v[224:227], v237 offset:32
	s_waitcnt lgkmcnt(3)
	v_mfma_f32_32x32x16_bf16 v[32:47], v[212:215], v[120:123], v[32:47]
	ds_read_b128 v[228:231], v237 offset:64
	s_waitcnt lgkmcnt(3)
	v_mfma_f32_32x32x16_bf16 v[32:47], v[216:219], v[124:127], v[32:47]
	ds_read_b128 v[232:235], v237 offset:96
	s_waitcnt lgkmcnt(3)
	v_mfma_f32_32x32x16_bf16 v[48:63], v[220:223], v[112:115], 0
	ds_read_b128 v[204:207], v241 offset:0
	s_waitcnt lgkmcnt(3)
	v_mfma_f32_32x32x16_bf16 v[48:63], v[224:227], v[116:119], v[48:63]
	ds_read_b128 v[208:211], v241 offset:32
	s_waitcnt lgkmcnt(3)
	v_mfma_f32_32x32x16_bf16 v[48:63], v[228:231], v[120:123], v[48:63]
	ds_read_b128 v[212:215], v241 offset:64
	s_waitcnt lgkmcnt(3)
	v_mfma_f32_32x32x16_bf16 v[48:63], v[232:235], v[124:127], v[48:63]
	ds_read_b128 v[216:219], v241 offset:96
	s_waitcnt lgkmcnt(3)
	v_mfma_f32_32x32x16_bf16 v[144:159], v[204:207], v[112:115], 0
	ds_read_b128 v[220:223], v242 offset:0
	s_waitcnt lgkmcnt(3)
	v_mfma_f32_32x32x16_bf16 v[144:159], v[208:211], v[116:119], v[144:159]
	ds_read_b128 v[224:227], v242 offset:32
	s_waitcnt lgkmcnt(3)
	v_mfma_f32_32x32x16_bf16 v[144:159], v[212:215], v[120:123], v[144:159]
	ds_read_b128 v[228:231], v242 offset:64
	s_waitcnt lgkmcnt(3)
	v_mfma_f32_32x32x16_bf16 v[144:159], v[216:219], v[124:127], v[144:159]
	ds_read_b128 v[232:235], v242 offset:96
	v_cmp_le_i32_e64 s[98:99], v240, 0
	v_max3_f32 v246, v48, v49, v50
	v_cmp_le_i32_e64 s[100:101], v240, 1
	v_max3_f32 v246, v246, v51, v52
	v_cmp_le_i32_e64 vcc, v240, 2
	v_max3_f32 v246, v246, v53, v54
	s_waitcnt lgkmcnt(3)
	v_mfma_f32_32x32x16_bf16 v[160:175], v[220:223], v[112:115], 0
	ds_read_b128 v[204:207], v243 offset:0
	v_cndmask_b32_e64 v32, v179, v32, s[98:99]
	v_max3_f32 v246, v246, v55, v56
	v_cmp_le_i32_e64 s[98:99], v240, 3
	v_max3_f32 v246, v246, v57, v58
	v_cndmask_b32_e64 v33, v179, v33, s[100:101]
	v_max3_f32 v246, v246, v59, v60
	s_waitcnt lgkmcnt(3)
	v_mfma_f32_32x32x16_bf16 v[160:175], v[224:227], v[116:119], v[160:175]
	ds_read_b128 v[208:211], v243 offset:32
	v_cmp_le_i32_e64 s[100:101], v240, 8
	v_max3_f32 v246, v246, v61, v62
	v_cndmask_b32_e64 v34, v179, v34, vcc
	v_max3_f32 v246, v246, v63, v63
	v_cmp_le_i32_e64 vcc, v240, 9
	v_cndmask_b32_e64 v35, v179, v35, s[98:99]
	s_waitcnt lgkmcnt(3)
	v_mfma_f32_32x32x16_bf16 v[160:175], v[228:231], v[120:123], v[160:175]
	ds_read_b128 v[212:215], v243 offset:64
	v_cmp_le_i32_e64 s[98:99], v240, 10
	v_cndmask_b32_e64 v36, v179, v36, s[100:101]
	v_cmp_le_i32_e64 s[100:101], v240, 11
	v_cndmask_b32_e64 v37, v179, v37, vcc
	v_cmp_le_i32_e64 vcc, v240, 16
	v_cndmask_b32_e64 v38, v179, v38, s[98:99]
	s_waitcnt lgkmcnt(3)
	v_mfma_f32_32x32x16_bf16 v[160:175], v[232:235], v[124:127], v[160:175]
	ds_read_b128 v[216:219], v243 offset:96
	v_cmp_le_i32_e64 s[98:99], v240, 17
	v_cndmask_b32_e64 v39, v179, v39, s[100:101]
	v_cmp_le_i32_e64 s[100:101], v240, 18
	v_cndmask_b32_e64 v40, v179, v40, vcc
	v_cmp_le_i32_e64 vcc, v240, 19
	v_cndmask_b32_e64 v41, v179, v41, s[98:99]
	v_cmp_le_i32_e64 s[98:99], v240, 24
	v_cndmask_b32_e64 v42, v179, v42, s[100:101]
	v_cmp_le_i32_e64 s[100:101], v240, 25
	v_cndmask_b32_e64 v43, v179, v43, vcc
	v_cmp_le_i32_e64 vcc, v240, 26
	v_cndmask_b32_e64 v44, v179, v44, s[98:99]
	v_cmp_le_i32_e64 s[98:99], v240, 27
	v_cndmask_b32_e64 v45, v179, v45, s[100:101]
	v_cndmask_b32_e64 v46, v179, v46, vcc
	v_cndmask_b32_e64 v47, v179, v47, s[98:99]
	v_max3_f32 v247, v144, v145, v146
	v_max3_f32 v248, v32, v33, v34
	v_max3_f32 v247, v247, v147, v148
	v_max3_f32 v248, v248, v35, v36
	s_waitcnt lgkmcnt(3)
	v_mfma_f32_32x32x16_bf16 v[188:203], v[204:207], v[112:115], 0
	ds_read_b64_tr_b16 v[220:221], v244 offset:9216
	ds_read_b64_tr_b16 v[222:223], v244 offset:9728
	v_max3_f32 v247, v247, v149, v150
	v_max3_f32 v248, v248, v37, v38
	v_max3_f32 v247, v247, v151, v152
	v_max3_f32 v248, v248, v39, v40
	s_waitcnt lgkmcnt(4)
	v_mfma_f32_32x32x16_bf16 v[188:203], v[208:211], v[116:119], v[188:203]
	ds_read_b64_tr_b16 v[224:225], v244 offset:13312
	ds_read_b64_tr_b16 v[226:227], v244 offset:13824
	v_max3_f32 v247, v247, v153, v154
	v_max3_f32 v248, v248, v41, v42
	v_max3_f32 v247, v247, v155, v156
	v_max3_f32 v248, v248, v43, v44
	s_waitcnt lgkmcnt(5)
	v_mfma_f32_32x32x16_bf16 v[188:203], v[212:215], v[120:123], v[188:203]
	ds_read_b64_tr_b16 v[228:229], v244 offset:10240
	ds_read_b64_tr_b16 v[230:231], v244 offset:10752
	v_max3_f32 v247, v247, v157, v158
	v_max3_f32 v248, v248, v45, v46
	v_max3_f32 v247, v247, v159, v159
	v_max3_f32 v248, v248, v47, v47
	s_waitcnt lgkmcnt(6)
	v_mfma_f32_32x32x16_bf16 v[188:203], v[216:219], v[124:127], v[188:203]
	ds_read_b64_tr_b16 v[232:233], v244 offset:14336
	ds_read_b64_tr_b16 v[234:235], v244 offset:14848
	v_max3_f32 v249, v160, v161, v162
	v_max3_f32 v249, v249, v163, v164
	v_max3_f32 v249, v249, v165, v166
	v_max3_f32 v249, v249, v167, v168
	v_max3_f32 v249, v249, v169, v170
	v_max3_f32 v249, v249, v171, v172
	v_max3_f32 v249, v249, v173, v174
	v_max3_f32 v249, v249, v175, v175
	v_cmp_ge_i32_e64 s[98:99], v240, 0
	v_cmp_ge_i32_e64 s[100:101], v240, 1
	v_cmp_ge_i32_e64 vcc, v240, 2
	v_cndmask_b32_e64 v188, v179, v188, s[98:99]
	v_cmp_ge_i32_e64 s[98:99], v240, 3
	v_cndmask_b32_e64 v189, v179, v189, s[100:101]
	v_cmp_ge_i32_e64 s[100:101], v240, 8
	v_cndmask_b32_e64 v190, v179, v190, vcc
	v_cmp_ge_i32_e64 vcc, v240, 9
	v_cndmask_b32_e64 v191, v179, v191, s[98:99]
	v_cmp_ge_i32_e64 s[98:99], v240, 10
	v_cndmask_b32_e64 v192, v179, v192, s[100:101]
	v_cmp_ge_i32_e64 s[100:101], v240, 11
	v_cndmask_b32_e64 v193, v179, v193, vcc
	v_cmp_ge_i32_e64 vcc, v240, 16
	v_cndmask_b32_e64 v194, v179, v194, s[98:99]
	v_cmp_ge_i32_e64 s[98:99], v240, 17
	v_cndmask_b32_e64 v195, v179, v195, s[100:101]
	v_cmp_ge_i32_e64 s[100:101], v240, 18
	v_cndmask_b32_e64 v196, v179, v196, vcc
	v_cmp_ge_i32_e64 vcc, v240, 19
	v_cndmask_b32_e64 v197, v179, v197, s[98:99]
	v_cmp_ge_i32_e64 s[98:99], v240, 24
	v_cndmask_b32_e64 v198, v179, v198, s[100:101]
	v_cmp_ge_i32_e64 s[100:101], v240, 25
	v_cndmask_b32_e64 v199, v179, v199, vcc
	v_cmp_ge_i32_e64 vcc, v240, 26
	v_cndmask_b32_e64 v200, v179, v200, s[98:99]
	v_cmp_ge_i32_e64 s[98:99], v240, 27
	v_cndmask_b32_e64 v201, v179, v201, s[100:101]
	v_cndmask_b32_e64 v202, v179, v202, vcc
	v_cndmask_b32_e64 v203, v179, v203, s[98:99]
	v_max3_f32 v249, v249, v188, v189
	v_max3_f32 v249, v249, v190, v191
	v_max3_f32 v249, v249, v192, v193
	v_max3_f32 v249, v249, v194, v195
	v_max3_f32 v249, v249, v196, v197
	v_max3_f32 v249, v249, v198, v199
	v_max3_f32 v249, v249, v200, v201
	v_max3_f32 v249, v249, v202, v203
	v_max3_f32 v246, v246, v247, v248
	v_max_f32_e32 v246, v246, v249
	v_mov_b32_e32 v247, v246
	s_nop 1
	v_permlane32_swap_b32_e32 v246, v247
	v_max_f32_e32 v246, v246, v247
	v_mul_f32_e32 v250, s49, v246
	v_fma_f32 v32, v32, s49, -v250
	v_fma_f32 v33, v33, s49, -v250
	v_fma_f32 v34, v34, s49, -v250
	v_exp_f32_e32 v32, v32
	v_fma_f32 v35, v35, s49, -v250
	v_exp_f32_e32 v33, v33
	v_fma_f32 v36, v36, s49, -v250
	v_exp_f32_e32 v34, v34
	v_fma_f32 v37, v37, s49, -v250
	v_exp_f32_e32 v35, v35
	v_fma_f32 v38, v38, s49, -v250
	v_exp_f32_e32 v36, v36
	v_mov_b64_e32 v[246:247], v[32:33]
	v_fma_f32 v39, v39, s49, -v250
	v_exp_f32_e32 v37, v37
	v_fma_f32 v40, v40, s49, -v250
	v_exp_f32_e32 v38, v38
	v_mov_b64_e32 v[248:249], v[34:35]
	v_fma_f32 v41, v41, s49, -v250
	v_exp_f32_e32 v39, v39
	v_fma_f32 v42, v42, s49, -v250
	v_exp_f32_e32 v40, v40
	v_pk_add_f32 v[246:247], v[246:247], v[36:37]
	v_fma_f32 v43, v43, s49, -v250
	v_exp_f32_e32 v41, v41
	v_fma_f32 v44, v44, s49, -v250
	v_exp_f32_e32 v42, v42
	v_pk_add_f32 v[248:249], v[248:249], v[38:39]
	v_fma_f32 v45, v45, s49, -v250
	v_exp_f32_e32 v43, v43
	v_fma_f32 v46, v46, s49, -v250
	v_exp_f32_e32 v44, v44
	v_pk_add_f32 v[246:247], v[246:247], v[40:41]
	v_fma_f32 v47, v47, s49, -v250
	v_exp_f32_e32 v45, v45
	v_exp_f32_e32 v46, v46
	v_pk_add_f32 v[248:249], v[248:249], v[42:43]
	v_exp_f32_e32 v47, v47
	v_pk_add_f32 v[246:247], v[246:247], v[44:45]
	v_pk_add_f32 v[248:249], v[248:249], v[46:47]
	v_cvt_pk_bf16_f32 v32, v32, v33
	v_cvt_pk_bf16_f32 v33, v34, v35
	v_cvt_pk_bf16_f32 v34, v36, v37
	v_cvt_pk_bf16_f32 v35, v38, v39
	v_cvt_pk_bf16_f32 v36, v40, v41
	v_cvt_pk_bf16_f32 v37, v42, v43
	v_cvt_pk_bf16_f32 v38, v44, v45
	v_cvt_pk_bf16_f32 v39, v46, v47
	v_fma_f32 v48, v48, s49, -v250
	v_fma_f32 v49, v49, s49, -v250
	v_fma_f32 v50, v50, s49, -v250
	v_exp_f32_e32 v48, v48
	v_fma_f32 v51, v51, s49, -v250
	v_exp_f32_e32 v49, v49
	v_fma_f32 v52, v52, s49, -v250
	v_exp_f32_e32 v50, v50
	s_waitcnt lgkmcnt(6)
	v_mfma_f32_32x32x16_bf16 v[16:31], v[220:223], v[32:35], v[16:31]
	ds_read_b64_tr_b16 v[204:205], v251 offset:9216
	ds_read_b64_tr_b16 v[206:207], v251 offset:9728
	v_fma_f32 v53, v53, s49, -v250
	v_exp_f32_e32 v51, v51
	v_fma_f32 v54, v54, s49, -v250
	v_exp_f32_e32 v52, v52
	v_pk_add_f32 v[246:247], v[246:247], v[48:49]
	v_fma_f32 v55, v55, s49, -v250
	v_exp_f32_e32 v53, v53
	v_fma_f32 v56, v56, s49, -v250
	s_waitcnt lgkmcnt(6)
	v_mfma_f32_32x32x16_bf16 v[0:15], v[224:227], v[32:35], v[0:15]
	ds_read_b64_tr_b16 v[208:209], v251 offset:13312
	ds_read_b64_tr_b16 v[210:211], v251 offset:13824
	v_exp_f32_e32 v54, v54
	v_pk_add_f32 v[248:249], v[248:249], v[50:51]
	v_fma_f32 v57, v57, s49, -v250
	v_exp_f32_e32 v55, v55
	v_fma_f32 v58, v58, s49, -v250
	v_exp_f32_e32 v56, v56
	v_pk_add_f32 v[246:247], v[246:247], v[52:53]
	v_fma_f32 v59, v59, s49, -v250
	s_waitcnt lgkmcnt(6)
	v_mfma_f32_32x32x16_bf16 v[16:31], v[228:231], v[36:39], v[16:31]
	ds_read_b64_tr_b16 v[212:213], v251 offset:10240
	ds_read_b64_tr_b16 v[214:215], v251 offset:10752
	v_exp_f32_e32 v57, v57
	v_fma_f32 v60, v60, s49, -v250
	v_exp_f32_e32 v58, v58
	v_pk_add_f32 v[248:249], v[248:249], v[54:55]
	v_fma_f32 v61, v61, s49, -v250
	v_exp_f32_e32 v59, v59
	v_fma_f32 v62, v62, s49, -v250
	v_exp_f32_e32 v60, v60
	s_waitcnt lgkmcnt(6)
	v_mfma_f32_32x32x16_bf16 v[0:15], v[232:235], v[36:39], v[0:15]
	ds_read_b64_tr_b16 v[216:217], v251 offset:14336
	ds_read_b64_tr_b16 v[218:219], v251 offset:14848
	v_pk_add_f32 v[246:247], v[246:247], v[56:57]
	v_fma_f32 v63, v63, s49, -v250
	v_exp_f32_e32 v61, v61
	v_exp_f32_e32 v62, v62
	v_pk_add_f32 v[248:249], v[248:249], v[58:59]
	v_exp_f32_e32 v63, v63
	v_pk_add_f32 v[246:247], v[246:247], v[60:61]
	v_pk_add_f32 v[248:249], v[248:249], v[62:63]
	v_cvt_pk_bf16_f32 v48, v48, v49
	v_cvt_pk_bf16_f32 v49, v50, v51
	v_cvt_pk_bf16_f32 v50, v52, v53
	v_cvt_pk_bf16_f32 v51, v54, v55
	v_cvt_pk_bf16_f32 v52, v56, v57
	v_cvt_pk_bf16_f32 v53, v58, v59
	v_cvt_pk_bf16_f32 v54, v60, v61
	v_cvt_pk_bf16_f32 v55, v62, v63
	v_fma_f32 v144, v144, s49, -v250
	v_fma_f32 v145, v145, s49, -v250
	v_fma_f32 v146, v146, s49, -v250
	v_exp_f32_e32 v144, v144
	v_fma_f32 v147, v147, s49, -v250
	v_exp_f32_e32 v145, v145
	v_fma_f32 v148, v148, s49, -v250
	v_exp_f32_e32 v146, v146
	s_waitcnt lgkmcnt(6)
	v_mfma_f32_32x32x16_bf16 v[16:31], v[204:207], v[48:51], v[16:31]
	ds_read_b64_tr_b16 v[220:221], v252 offset:9216
	ds_read_b64_tr_b16 v[222:223], v252 offset:9728
	v_fma_f32 v149, v149, s49, -v250
	v_exp_f32_e32 v147, v147
	v_fma_f32 v150, v150, s49, -v250
	v_exp_f32_e32 v148, v148
	v_pk_add_f32 v[246:247], v[246:247], v[144:145]
	v_fma_f32 v151, v151, s49, -v250
	v_exp_f32_e32 v149, v149
	v_fma_f32 v152, v152, s49, -v250
	s_waitcnt lgkmcnt(6)
	v_mfma_f32_32x32x16_bf16 v[0:15], v[208:211], v[48:51], v[0:15]
	ds_read_b64_tr_b16 v[224:225], v252 offset:13312
	ds_read_b64_tr_b16 v[226:227], v252 offset:13824
	v_exp_f32_e32 v150, v150
	v_pk_add_f32 v[248:249], v[248:249], v[146:147]
	v_fma_f32 v153, v153, s49, -v250
	v_exp_f32_e32 v151, v151
	v_fma_f32 v154, v154, s49, -v250
	v_exp_f32_e32 v152, v152
	v_pk_add_f32 v[246:247], v[246:247], v[148:149]
	v_fma_f32 v155, v155, s49, -v250
	s_waitcnt lgkmcnt(6)
	v_mfma_f32_32x32x16_bf16 v[16:31], v[212:215], v[52:55], v[16:31]
	ds_read_b64_tr_b16 v[228:229], v252 offset:10240
	ds_read_b64_tr_b16 v[230:231], v252 offset:10752
	v_exp_f32_e32 v153, v153
	v_fma_f32 v156, v156, s49, -v250
	v_exp_f32_e32 v154, v154
	v_pk_add_f32 v[248:249], v[248:249], v[150:151]
	v_fma_f32 v157, v157, s49, -v250
	v_exp_f32_e32 v155, v155
	v_fma_f32 v158, v158, s49, -v250
	v_exp_f32_e32 v156, v156
	s_waitcnt lgkmcnt(6)
	v_mfma_f32_32x32x16_bf16 v[0:15], v[216:219], v[52:55], v[0:15]
	ds_read_b64_tr_b16 v[232:233], v252 offset:14336
	ds_read_b64_tr_b16 v[234:235], v252 offset:14848
	v_pk_add_f32 v[246:247], v[246:247], v[152:153]
	v_fma_f32 v159, v159, s49, -v250
	v_exp_f32_e32 v157, v157
	v_exp_f32_e32 v158, v158
	v_pk_add_f32 v[248:249], v[248:249], v[154:155]
	v_exp_f32_e32 v159, v159
	v_pk_add_f32 v[246:247], v[246:247], v[156:157]
	v_pk_add_f32 v[248:249], v[248:249], v[158:159]
	v_cvt_pk_bf16_f32 v144, v144, v145
	v_cvt_pk_bf16_f32 v145, v146, v147
	v_cvt_pk_bf16_f32 v146, v148, v149
	v_cvt_pk_bf16_f32 v147, v150, v151
	v_cvt_pk_bf16_f32 v148, v152, v153
	v_cvt_pk_bf16_f32 v149, v154, v155
	v_cvt_pk_bf16_f32 v150, v156, v157
	v_cvt_pk_bf16_f32 v151, v158, v159
	v_fma_f32 v160, v160, s49, -v250
	v_fma_f32 v161, v161, s49, -v250
	v_fma_f32 v162, v162, s49, -v250
	v_exp_f32_e32 v160, v160
	v_fma_f32 v163, v163, s49, -v250
	v_exp_f32_e32 v161, v161
	v_fma_f32 v164, v164, s49, -v250
	v_exp_f32_e32 v162, v162
	s_waitcnt lgkmcnt(6)
	v_mfma_f32_32x32x16_bf16 v[16:31], v[220:223], v[144:147], v[16:31]
	ds_read_b64_tr_b16 v[204:205], v253 offset:9216
	ds_read_b64_tr_b16 v[206:207], v253 offset:9728
	v_fma_f32 v165, v165, s49, -v250
	v_exp_f32_e32 v163, v163
	v_fma_f32 v166, v166, s49, -v250
	v_exp_f32_e32 v164, v164
	v_pk_add_f32 v[246:247], v[246:247], v[160:161]
	v_fma_f32 v167, v167, s49, -v250
	v_exp_f32_e32 v165, v165
	v_fma_f32 v168, v168, s49, -v250
	s_waitcnt lgkmcnt(6)
	v_mfma_f32_32x32x16_bf16 v[0:15], v[224:227], v[144:147], v[0:15]
	ds_read_b64_tr_b16 v[208:209], v253 offset:13312
	ds_read_b64_tr_b16 v[210:211], v253 offset:13824
	v_exp_f32_e32 v166, v166
	v_pk_add_f32 v[248:249], v[248:249], v[162:163]
	v_fma_f32 v169, v169, s49, -v250
	v_exp_f32_e32 v167, v167
	v_fma_f32 v170, v170, s49, -v250
	v_exp_f32_e32 v168, v168
	v_pk_add_f32 v[246:247], v[246:247], v[164:165]
	v_fma_f32 v171, v171, s49, -v250
	s_waitcnt lgkmcnt(6)
	v_mfma_f32_32x32x16_bf16 v[16:31], v[228:231], v[148:151], v[16:31]
	ds_read_b64_tr_b16 v[212:213], v253 offset:10240
	ds_read_b64_tr_b16 v[214:215], v253 offset:10752
	v_exp_f32_e32 v169, v169
	v_fma_f32 v172, v172, s49, -v250
	v_exp_f32_e32 v170, v170
	v_pk_add_f32 v[248:249], v[248:249], v[166:167]
	v_fma_f32 v173, v173, s49, -v250
	v_exp_f32_e32 v171, v171
	v_fma_f32 v174, v174, s49, -v250
	v_exp_f32_e32 v172, v172
	s_waitcnt lgkmcnt(6)
	v_mfma_f32_32x32x16_bf16 v[0:15], v[232:235], v[148:151], v[0:15]
	ds_read_b64_tr_b16 v[216:217], v253 offset:14336
	ds_read_b64_tr_b16 v[218:219], v253 offset:14848
	v_pk_add_f32 v[246:247], v[246:247], v[168:169]
	v_fma_f32 v175, v175, s49, -v250
	v_exp_f32_e32 v173, v173
	v_exp_f32_e32 v174, v174
	v_pk_add_f32 v[248:249], v[248:249], v[170:171]
	v_exp_f32_e32 v175, v175
	v_pk_add_f32 v[246:247], v[246:247], v[172:173]
	v_pk_add_f32 v[248:249], v[248:249], v[174:175]
	v_cvt_pk_bf16_f32 v160, v160, v161
	v_cvt_pk_bf16_f32 v161, v162, v163
	v_cvt_pk_bf16_f32 v162, v164, v165
	v_cvt_pk_bf16_f32 v163, v166, v167
	v_cvt_pk_bf16_f32 v164, v168, v169
	v_cvt_pk_bf16_f32 v165, v170, v171
	v_cvt_pk_bf16_f32 v166, v172, v173
	v_cvt_pk_bf16_f32 v167, v174, v175
	v_fma_f32 v188, v188, s49, -v250
	v_fma_f32 v189, v189, s49, -v250
	v_fma_f32 v190, v190, s49, -v250
	v_exp_f32_e32 v188, v188
	v_fma_f32 v191, v191, s49, -v250
	v_exp_f32_e32 v189, v189
	v_fma_f32 v192, v192, s49, -v250
	v_exp_f32_e32 v190, v190
	s_waitcnt lgkmcnt(6)
	v_mfma_f32_32x32x16_bf16 v[16:31], v[204:207], v[160:163], v[16:31]
	ds_read_b64_tr_b16 v[220:221], v254 offset:9216
	ds_read_b64_tr_b16 v[222:223], v254 offset:9728
	v_fma_f32 v193, v193, s49, -v250
	v_exp_f32_e32 v191, v191
	v_fma_f32 v194, v194, s49, -v250
	v_exp_f32_e32 v192, v192
	v_pk_add_f32 v[246:247], v[246:247], v[188:189]
	v_fma_f32 v195, v195, s49, -v250
	v_exp_f32_e32 v193, v193
	v_fma_f32 v196, v196, s49, -v250
	s_waitcnt lgkmcnt(6)
	v_mfma_f32_32x32x16_bf16 v[0:15], v[208:211], v[160:163], v[0:15]
	ds_read_b64_tr_b16 v[224:225], v254 offset:13312
	ds_read_b64_tr_b16 v[226:227], v254 offset:13824
	v_exp_f32_e32 v194, v194
	v_pk_add_f32 v[248:249], v[248:249], v[190:191]
	v_fma_f32 v197, v197, s49, -v250
	v_exp_f32_e32 v195, v195
	v_fma_f32 v198, v198, s49, -v250
	v_exp_f32_e32 v196, v196
	v_pk_add_f32 v[246:247], v[246:247], v[192:193]
	v_fma_f32 v199, v199, s49, -v250
	s_waitcnt lgkmcnt(6)
	v_mfma_f32_32x32x16_bf16 v[16:31], v[212:215], v[164:167], v[16:31]
	ds_read_b64_tr_b16 v[228:229], v254 offset:10240
	ds_read_b64_tr_b16 v[230:231], v254 offset:10752
	v_exp_f32_e32 v197, v197
	v_fma_f32 v200, v200, s49, -v250
	v_exp_f32_e32 v198, v198
	v_pk_add_f32 v[248:249], v[248:249], v[194:195]
	v_fma_f32 v201, v201, s49, -v250
	v_exp_f32_e32 v199, v199
	v_fma_f32 v202, v202, s49, -v250
	v_exp_f32_e32 v200, v200
	s_waitcnt lgkmcnt(6)
	v_mfma_f32_32x32x16_bf16 v[0:15], v[216:219], v[164:167], v[0:15]
	ds_read_b64_tr_b16 v[232:233], v254 offset:14336
	ds_read_b64_tr_b16 v[234:235], v254 offset:14848
	v_pk_add_f32 v[246:247], v[246:247], v[196:197]
	v_fma_f32 v203, v203, s49, -v250
	v_exp_f32_e32 v201, v201
	v_exp_f32_e32 v202, v202
	v_pk_add_f32 v[248:249], v[248:249], v[198:199]
	v_exp_f32_e32 v203, v203
	v_pk_add_f32 v[246:247], v[246:247], v[200:201]
	v_pk_add_f32 v[248:249], v[248:249], v[202:203]
	v_cvt_pk_bf16_f32 v188, v188, v189
	v_cvt_pk_bf16_f32 v189, v190, v191
	v_cvt_pk_bf16_f32 v190, v192, v193
	v_cvt_pk_bf16_f32 v191, v194, v195
	v_cvt_pk_bf16_f32 v192, v196, v197
	v_cvt_pk_bf16_f32 v193, v198, v199
	v_cvt_pk_bf16_f32 v194, v200, v201
	v_cvt_pk_bf16_f32 v195, v202, v203
	v_pk_add_f32 v[246:247], v[246:247], v[248:249]
	s_waitcnt lgkmcnt(6)
	v_mfma_f32_32x32x16_bf16 v[16:31], v[220:223], v[188:191], v[16:31]
	s_waitcnt lgkmcnt(4)
	v_mfma_f32_32x32x16_bf16 v[0:15], v[224:227], v[188:191], v[0:15]
	v_add_f32_e32 v182, v246, v247
	v_mov_b32_e32 v187, v250
	s_waitcnt lgkmcnt(2)
	v_mfma_f32_32x32x16_bf16 v[16:31], v[228:231], v[192:195], v[16:31]
	s_waitcnt lgkmcnt(0)
	v_mfma_f32_32x32x16_bf16 v[0:15], v[232:235], v[192:195], v[0:15]
	s_branch .LBB0_2000

	.amdhsa_kernel _Z8mega_fwd6Params
		.amdhsa_group_segment_fixed_size 0
		.amdhsa_private_segment_fixed_size 0
		.amdhsa_kernarg_size 400
		.amdhsa_user_sgpr_count 2
		.amdhsa_user_sgpr_dispatch_ptr 0
		.amdhsa_user_sgpr_queue_ptr 0
		.amdhsa_user_sgpr_kernarg_segment_ptr 1
		.amdhsa_user_sgpr_dispatch_id 0
		.amdhsa_user_sgpr_kernarg_preload_length 0
		.amdhsa_user_sgpr_kernarg_preload_offset 0
		.amdhsa_user_sgpr_private_segment_size 0
		.amdhsa_uses_dynamic_stack 0
		.amdhsa_enable_private_segment 0
		.amdhsa_system_sgpr_workgroup_id_x 1
		.amdhsa_system_sgpr_workgroup_id_y 0
		.amdhsa_system_sgpr_workgroup_id_z 0
		.amdhsa_system_sgpr_workgroup_info 0
		.amdhsa_system_vgpr_workitem_id 2
		.amdhsa_next_free_vgpr 256
		.amdhsa_next_free_sgpr 102
		.amdhsa_accum_offset 256
		.amdhsa_reserve_vcc 1
		.amdhsa_float_round_mode_32 0
		.amdhsa_float_round_mode_16_64 0
		.amdhsa_float_denorm_mode_32 3
		.amdhsa_float_denorm_mode_16_64 3
		.amdhsa_dx10_clamp 1
		.amdhsa_ieee_mode 1
		.amdhsa_fp16_overflow 0
		.amdhsa_tg_split 0
		.amdhsa_exception_fp_ieee_invalid_op 0
		.amdhsa_exception_fp_denorm_src 0
		.amdhsa_exception_fp_ieee_div_zero 0
		.amdhsa_exception_fp_ieee_overflow 0
		.amdhsa_exception_fp_ieee_underflow 0
		.amdhsa_exception_fp_ieee_inexact 0
		.amdhsa_exception_int_div_zero 0
	.end_amdhsa_kernel

amdhsa.kernels:
  - .agpr_count:     0
    .args:
      - .offset:         0
        .size:           144
        .value_kind:     by_value
      - .offset:         144
        .size:           4
        .value_kind:     hidden_block_count_x
      - .offset:         148
        .size:           4
        .value_kind:     hidden_block_count_y
      - .offset:         152
        .size:           4
        .value_kind:     hidden_block_count_z
      - .offset:         156
        .size:           2
        .value_kind:     hidden_group_size_x
      - .offset:         158
        .size:           2
        .value_kind:     hidden_group_size_y
      - .offset:         160
        .size:           2
        .value_kind:     hidden_group_size_z
      - .offset:         162
        .size:           2
        .value_kind:     hidden_remainder_x
      - .offset:         164
        .size:           2
        .value_kind:     hidden_remainder_y
      - .offset:         166
        .size:           2
        .value_kind:     hidden_remainder_z
      - .offset:         184
        .size:           8
        .value_kind:     hidden_global_offset_x
      - .offset:         192
        .size:           8
        .value_kind:     hidden_global_offset_y
      - .offset:         200
        .size:           8
        .value_kind:     hidden_global_offset_z
      - .offset:         208
        .size:           2
        .value_kind:     hidden_grid_dims
      - .offset:         232
        .size:           8
        .value_kind:     hidden_multigrid_sync_arg
      - .offset:         264
        .size:           4
        .value_kind:     hidden_dynamic_lds_size
    .group_segment_fixed_size: 0
    .kernarg_segment_align: 8
    .kernarg_segment_size: 400
    .language:       OpenCL C
    .language_version:
      - 2
      - 0
    .max_flat_workgroup_size: 512
    .name:           _Z8mega_fwd6Params
    .private_segment_fixed_size: 0
    .sgpr_count:     108
    .sgpr_spill_count: 56
    .symbol:         _Z8mega_fwd6Params.kd
    .uniform_work_group_size: 1
    .uses_dynamic_stack: false
    .vgpr_count:     256
    .vgpr_spill_count: 0
    .wavefront_size: 64
